# static s_setprio 1 for waves 4-7 at the start of the two attention / SSD phases (the tile loops run in lockstep; priority de-phases the two waves of a SIMD)
# speedup vs baseline: 1.0332x; 1.0009x over previous
.LBB0_502:
	s_or_b64 exec, exec, s[6:7]
	v_mov_b32_e32 v0, s88
	v_readlane_b32 s0, v254, 17
	s_waitcnt lgkmcnt(0)
	s_barrier
	v_readfirstlane_b32 s100, v247
	s_cmpk_lt_u32 s100, 0x100
	s_cbranch_scc1 .Lprio_skip1
	s_setprio 1
.Lprio_skip1:
	v_readlane_b32 s1, v254, 18
	v_readfirstlane_b32 s44, v0
	s_andn2_b64 vcc, exec, s[0:1]
	v_cndmask_b32_e64 v0, 0, 1, s[0:1]
	v_cmp_ne_u32_e64 s[38:39], 1, v0
	s_mov_b64 s[6:7], -1
	s_cbranch_vccnz .LBB0_613
	s_cmpk_gt_i32 s44, 0x54f
	s_cbranch_scc1 .LBB0_612
	s_lshl_b32 s0, s44, 5
	s_lshl_b32 s1, s44, 1
	s_lshl_b32 s5, s44, 7
	s_add_i32 s0, s0, 0xffff6e00
	s_addk_i32 s1, 0xfae0
	s_add_i32 s4, s44, 0xfffffd70
	s_addk_i32 s5, 0xb800
	s_add_i32 s20, s44, 0xffffff70
	s_mov_b32 s6, s44
	s_branch .LBB0_506

.LBB0_820:
	s_or_b64 exec, exec, s[6:7]
	v_mov_b32_e32 v0, s88
	s_waitcnt lgkmcnt(0)
	s_barrier
	v_readfirstlane_b32 s100, v247
	s_cmpk_lt_u32 s100, 0x100
	s_cbranch_scc1 .Lprio_skip2
	s_setprio 1
.Lprio_skip2:
	s_and_b64 vcc, exec, s[38:39]
	v_readfirstlane_b32 s40, v0
	s_mov_b64 s[6:7], -1
	s_cbranch_vccnz .LBB0_883
	s_cmpk_gt_i32 s40, 0x28f
	s_cbranch_scc1 .LBB0_882
	s_mov_b32 s8, s40
	s_branch .LBB0_824

	.amdhsa_kernel _Z10hybrid_fwd6Params
		.amdhsa_group_segment_fixed_size 16
		.amdhsa_private_segment_fixed_size 0
		.amdhsa_kernarg_size 512
		.amdhsa_user_sgpr_count 2
		.amdhsa_user_sgpr_dispatch_ptr 0
		.amdhsa_user_sgpr_queue_ptr 0
		.amdhsa_user_sgpr_kernarg_segment_ptr 1
		.amdhsa_user_sgpr_dispatch_id 0
		.amdhsa_user_sgpr_kernarg_preload_length 0
		.amdhsa_user_sgpr_kernarg_preload_offset 0
		.amdhsa_user_sgpr_private_segment_size 0
		.amdhsa_uses_dynamic_stack 0
		.amdhsa_enable_private_segment 0
		.amdhsa_system_sgpr_workgroup_id_x 1
		.amdhsa_system_sgpr_workgroup_id_y 0
		.amdhsa_system_sgpr_workgroup_id_z 0
		.amdhsa_system_sgpr_workgroup_info 0
		.amdhsa_system_vgpr_workitem_id 2
		.amdhsa_next_free_vgpr 256
		.amdhsa_next_free_sgpr 102
		.amdhsa_accum_offset 256
		.amdhsa_reserve_vcc 1
		.amdhsa_float_round_mode_32 0
		.amdhsa_float_round_mode_16_64 0
		.amdhsa_float_denorm_mode_32 3
		.amdhsa_float_denorm_mode_16_64 3
		.amdhsa_dx10_clamp 1
		.amdhsa_ieee_mode 1
		.amdhsa_fp16_overflow 0
		.amdhsa_tg_split 0
		.amdhsa_exception_fp_ieee_invalid_op 0
		.amdhsa_exception_fp_denorm_src 0
		.amdhsa_exception_fp_ieee_div_zero 0
		.amdhsa_exception_fp_ieee_overflow 0
		.amdhsa_exception_fp_ieee_underflow 0
		.amdhsa_exception_fp_ieee_inexact 0
		.amdhsa_exception_int_div_zero 0
	.end_amdhsa_kernel

amdhsa.kernels:
  - .agpr_count:     0
    .args:
      - .offset:         0
        .size:           256
        .value_kind:     by_value
      - .offset:         256
        .size:           4
        .value_kind:     hidden_block_count_x
      - .offset:         260
        .size:           4
        .value_kind:     hidden_block_count_y
      - .offset:         264
        .size:           4
        .value_kind:     hidden_block_count_z
      - .offset:         268
        .size:           2
        .value_kind:     hidden_group_size_x
      - .offset:         270
        .size:           2
        .value_kind:     hidden_group_size_y
      - .offset:         272
        .size:           2
        .value_kind:     hidden_group_size_z
      - .offset:         274
        .size:           2
        .value_kind:     hidden_remainder_x
      - .offset:         276
        .size:           2
        .value_kind:     hidden_remainder_y
      - .offset:         278
        .size:           2
        .value_kind:     hidden_remainder_z
      - .offset:         296
        .size:           8
        .value_kind:     hidden_global_offset_x
      - .offset:         304
        .size:           8
        .value_kind:     hidden_global_offset_y
      - .offset:         312
        .size:           8
        .value_kind:     hidden_global_offset_z
      - .offset:         320
        .size:           2
        .value_kind:     hidden_grid_dims
      - .offset:         344
        .size:           8
        .value_kind:     hidden_multigrid_sync_arg
      - .offset:         376
        .size:           4
        .value_kind:     hidden_dynamic_lds_size
    .group_segment_fixed_size: 16
    .kernarg_segment_align: 8
    .kernarg_segment_size: 512
    .language:       OpenCL C
    .language_version:
      - 2
      - 0
    .max_flat_workgroup_size: 512
    .name:           _Z10hybrid_fwd6Params
    .private_segment_fixed_size: 0
    .sgpr_count:     108
    .sgpr_spill_count: 159
    .symbol:         _Z10hybrid_fwd6Params.kd
    .uniform_work_group_size: 1
    .uses_dynamic_stack: false
    .vgpr_count:     256
    .vgpr_spill_count: 0
    .wavefront_size: 64
